# copy stores with default cache policy instead of nt
# speedup vs baseline: 1.0045x; 1.0045x over previous
.LBB0_36:
	v_cmp_gt_i32_e64 s[6:7], s43, v45
	v_add_u32_e32 v10, s71, v45
	v_cmp_gt_i32_e64 s[10:11], s43, v10
	v_cndmask_b32_e64 v0, v46, v45, s[6:7]
	v_add_u32_e32 v1, 0xffc02000, v0
	v_cmp_lt_i32_e64 s[4:5], s54, v0
	v_add_u32_e32 v14, s71, v10
	v_cmp_gt_i32_e64 s[14:15], s43, v14
	v_cndmask_b32_e64 v6, v0, v1, s[4:5]
	v_mul_hi_i32 v2, v6, s55
	v_add_u32_e32 v2, v2, v6
	v_lshrrev_b32_e32 v3, 31, v2
	v_ashrrev_i32_e32 v2, 18, v2
	v_add_u32_e32 v2, v2, v3
	v_ashrrev_i32_e32 v3, 31, v2
	v_lshlrev_b64 v[4:5], 19, v[2:3]
	v_mad_i32_i24 v2, v2, s58, v6
	v_ashrrev_i32_e32 v3, 31, v2
	v_lshl_add_u64 v[30:31], v[4:5], 0, v[2:3]
	v_cndmask_b32_e64 v4, v46, v10, s[10:11]
	v_add_u32_e32 v5, 0xffc02000, v4
	v_cmp_lt_i32_e64 s[8:9], s54, v4
	v_add_u32_e32 v18, s71, v14
	v_cmp_gt_i32_e64 s[18:19], s43, v18
	v_cndmask_b32_e64 v11, v4, v5, s[8:9]
	v_mul_hi_i32 v6, v11, s55
	v_add_u32_e32 v6, v6, v11
	v_lshrrev_b32_e32 v7, 31, v6
	v_ashrrev_i32_e32 v6, 18, v6
	v_add_u32_e32 v6, v6, v7
	v_ashrrev_i32_e32 v7, 31, v6
	v_lshlrev_b64 v[8:9], 19, v[6:7]
	v_mad_i32_i24 v6, v6, s58, v11
	v_ashrrev_i32_e32 v7, 31, v6
	v_lshl_add_u64 v[32:33], v[8:9], 0, v[6:7]
	v_cndmask_b32_e64 v8, v46, v14, s[14:15]
	v_add_u32_e32 v9, 0xffc02000, v8
	v_cmp_lt_i32_e64 s[12:13], s54, v8
	v_add_u32_e32 v22, s71, v18
	v_cmp_gt_i32_e64 s[22:23], s43, v22
	v_cndmask_b32_e64 v15, v8, v9, s[12:13]
	v_mul_hi_i32 v10, v15, s55
	v_add_u32_e32 v10, v10, v15
	v_lshrrev_b32_e32 v11, 31, v10
	v_ashrrev_i32_e32 v10, 18, v10
	v_add_u32_e32 v10, v10, v11
	v_ashrrev_i32_e32 v11, 31, v10
	v_lshlrev_b64 v[12:13], 19, v[10:11]
	v_mad_i32_i24 v10, v10, s58, v15
	v_ashrrev_i32_e32 v11, 31, v10
	v_lshl_add_u64 v[34:35], v[12:13], 0, v[10:11]
	v_cndmask_b32_e64 v12, v46, v18, s[18:19]
	v_add_u32_e32 v13, 0xffc02000, v12
	v_cmp_lt_i32_e64 s[16:17], s54, v12
	s_waitcnt vmcnt(1)
	v_add_u32_e32 v26, s71, v22
	v_cmp_gt_i32_e64 s[26:27], s43, v26
	v_cndmask_b32_e64 v19, v12, v13, s[16:17]
	v_mul_hi_i32 v14, v19, s55
	v_add_u32_e32 v14, v14, v19
	v_lshrrev_b32_e32 v15, 31, v14
	v_ashrrev_i32_e32 v14, 18, v14
	v_add_u32_e32 v14, v14, v15
	v_ashrrev_i32_e32 v15, 31, v14
	v_lshlrev_b64 v[16:17], 19, v[14:15]
	v_mad_i32_i24 v14, v14, s58, v19
	v_ashrrev_i32_e32 v15, 31, v14
	v_lshl_add_u64 v[36:37], v[16:17], 0, v[14:15]
	v_cndmask_b32_e64 v16, v46, v22, s[22:23]
	v_add_u32_e32 v17, 0xffc02000, v16
	v_cmp_lt_i32_e64 s[20:21], s54, v16
	v_add_u32_e32 v28, s71, v26
	v_cmp_gt_i32_e64 s[30:31], s43, v28
	v_cndmask_b32_e64 v23, v16, v17, s[20:21]
	v_mul_hi_i32 v18, v23, s55
	v_add_u32_e32 v18, v18, v23
	v_lshrrev_b32_e32 v19, 31, v18
	v_ashrrev_i32_e32 v18, 18, v18
	v_add_u32_e32 v18, v18, v19
	v_ashrrev_i32_e32 v19, 31, v18
	v_lshlrev_b64 v[20:21], 19, v[18:19]
	v_mad_i32_i24 v18, v18, s58, v23
	v_ashrrev_i32_e32 v19, 31, v18
	v_lshl_add_u64 v[38:39], v[20:21], 0, v[18:19]
	v_cndmask_b32_e64 v20, v46, v26, s[26:27]
	v_add_u32_e32 v21, 0xffc02000, v20
	v_cmp_lt_i32_e64 s[24:25], s54, v20
	v_cndmask_b32_e64 v1, v47, v48, s[4:5]
	v_cndmask_b32_e64 v0, v49, v50, s[4:5]
	v_cndmask_b32_e64 v27, v20, v21, s[24:25]
	v_mul_hi_i32 v22, v27, s55
	v_add_u32_e32 v22, v22, v27
	v_lshrrev_b32_e32 v23, 31, v22
	v_ashrrev_i32_e32 v22, 18, v22
	v_add_u32_e32 v22, v22, v23
	v_ashrrev_i32_e32 v23, 31, v22
	v_lshlrev_b64 v[24:25], 19, v[22:23]
	v_mad_i32_i24 v22, v22, s58, v27
	v_ashrrev_i32_e32 v23, 31, v22
	v_lshl_add_u64 v[40:41], v[24:25], 0, v[22:23]
	v_cndmask_b32_e64 v24, v46, v28, s[30:31]
	v_add_u32_e32 v25, 0xffc02000, v24
	v_cmp_lt_i32_e64 s[28:29], s54, v24
	v_lshl_add_u64 v[0:1], v[30:31], 4, v[0:1]
	v_add_co_u32_e32 v0, vcc, s59, v0
	v_cndmask_b32_e64 v53, v24, v25, s[28:29]
	v_mul_hi_i32 v26, v53, s55
	v_add_u32_e32 v26, v26, v53
	v_lshrrev_b32_e32 v27, 31, v26
	v_ashrrev_i32_e32 v26, 18, v26
	v_add_u32_e32 v26, v26, v27
	v_cndmask_b32_e64 v5, v47, v48, s[8:9]
	v_cndmask_b32_e64 v4, v49, v50, s[8:9]
	v_ashrrev_i32_e32 v27, 31, v26
	v_addc_co_u32_e32 v1, vcc, 0, v1, vcc
	v_lshl_add_u64 v[4:5], v[32:33], 4, v[4:5]
	v_lshlrev_b64 v[42:43], 19, v[26:27]
	v_mad_i32_i24 v26, v26, s58, v53
	v_add_u32_e32 v53, s42, v28
	v_add_co_u32_e32 v4, vcc, s59, v4
	v_cndmask_b32_e64 v9, v47, v48, s[12:13]
	v_cndmask_b32_e64 v8, v49, v50, s[12:13]
	v_cmp_lt_i32_e64 s[34:35], s54, v53
	v_add_u32_e32 v28, 0xffc02000, v53
	v_addc_co_u32_e32 v5, vcc, 0, v5, vcc
	v_lshl_add_u64 v[8:9], v[34:35], 4, v[8:9]
	v_cndmask_b32_e64 v28, v53, v28, s[34:35]
	v_add_co_u32_e32 v8, vcc, s59, v8
	v_cndmask_b32_e64 v13, v47, v48, s[16:17]
	v_cndmask_b32_e64 v12, v49, v50, s[16:17]
	v_mul_hi_i32 v54, v28, s55
	v_addc_co_u32_e32 v9, vcc, 0, v9, vcc
	v_lshl_add_u64 v[12:13], v[36:37], 4, v[12:13]
	v_add_u32_e32 v54, v54, v28
	v_add_co_u32_e32 v12, vcc, s59, v12
	v_cndmask_b32_e64 v17, v47, v48, s[20:21]
	v_cndmask_b32_e64 v16, v49, v50, s[20:21]
	v_lshrrev_b32_e32 v55, 31, v54
	v_ashrrev_i32_e32 v54, 18, v54
	v_addc_co_u32_e32 v13, vcc, 0, v13, vcc
	v_lshl_add_u64 v[16:17], v[38:39], 4, v[16:17]
	v_add_u32_e32 v54, v54, v55
	v_add_co_u32_e32 v16, vcc, s59, v16
	v_cndmask_b32_e64 v21, v47, v48, s[24:25]
	v_cndmask_b32_e64 v20, v49, v50, s[24:25]
	v_ashrrev_i32_e32 v55, 31, v54
	v_addc_co_u32_e32 v17, vcc, 0, v17, vcc
	v_lshl_add_u64 v[20:21], v[40:41], 4, v[20:21]
	v_ashrrev_i32_e32 v27, 31, v26
	v_lshlrev_b64 v[56:57], 19, v[54:55]
	v_mad_i32_i24 v54, v54, s58, v28
	v_add_co_u32_e32 v20, vcc, s59, v20
	v_cndmask_b32_e64 v25, v47, v48, s[28:29]
	v_cndmask_b32_e64 v24, v49, v50, s[28:29]
	v_lshl_add_u64 v[42:43], v[42:43], 0, v[26:27]
	v_ashrrev_i32_e32 v55, 31, v54
	v_addc_co_u32_e32 v21, vcc, 0, v21, vcc
	v_lshl_add_u64 v[24:25], v[42:43], 4, v[24:25]
	v_lshl_add_u64 v[54:55], v[56:57], 0, v[54:55]
	v_add_co_u32_e32 v24, vcc, s59, v24
	v_cndmask_b32_e64 v27, v47, v48, s[34:35]
	v_cndmask_b32_e64 v26, v49, v50, s[34:35]
	v_lshlrev_b64 v[58:59], 4, v[54:55]
	v_addc_co_u32_e32 v25, vcc, 0, v25, vcc
	v_lshl_add_u64 v[26:27], v[26:27], 0, v[58:59]
	v_add_co_u32_e32 v26, vcc, 0x4000, v26
	global_load_dwordx4 v[0:3], v[0:1], off nt
	s_nop 0
	v_addc_co_u32_e32 v27, vcc, 0, v27, vcc
	global_load_dwordx4 v[4:7], v[4:5], off nt
	v_cndmask_b32_e64 v28, v51, v52, s[34:35]
	global_load_dwordx4 v[8:11], v[8:9], off nt
	v_lshl_add_u64 v[60:61], s[66:67], 0, v[28:29]
	global_load_dwordx4 v[12:15], v[12:13], off nt
	v_lshl_add_u64 v[58:59], v[60:61], 0, v[58:59]
	global_load_dwordx4 v[16:19], v[16:17], off nt
	s_nop 0
	global_load_dwordx4 v[20:23], v[20:21], off nt
	s_nop 0
	global_load_dwordx4 v[54:57], v[26:27], off nt
	s_nop 0
	global_load_dwordx4 v[24:27], v[24:25], off nt
	s_waitcnt vmcnt(1)
	global_store_dwordx4 v[58:59], v[54:57], off
	s_and_saveexec_b64 s[34:35], s[6:7]
	s_cbranch_execz .LBB0_43
	v_cndmask_b32_e64 v28, v51, v52, s[4:5]
	v_lshl_add_u64 v[54:55], s[66:67], 0, v[28:29]
	v_lshl_add_u64 v[30:31], v[30:31], 4, v[54:55]
	global_store_dwordx4 v[30:31], v[0:3], off
	s_or_b64 exec, exec, s[34:35]
	s_and_saveexec_b64 s[4:5], s[10:11]
	s_cbranch_execnz .LBB0_44

.LBB0_39:
	v_cndmask_b32_e64 v28, v51, v52, s[12:13]
	v_lshl_add_u64 v[0:1], s[66:67], 0, v[28:29]
	v_lshl_add_u64 v[0:1], v[34:35], 4, v[0:1]
	global_store_dwordx4 v[0:1], v[8:11], off
	s_or_b64 exec, exec, s[4:5]
	s_and_saveexec_b64 s[4:5], s[18:19]
	s_cbranch_execnz .LBB0_46

.LBB0_41:
	v_cndmask_b32_e64 v28, v51, v52, s[20:21]
	v_lshl_add_u64 v[0:1], s[66:67], 0, v[28:29]
	v_lshl_add_u64 v[0:1], v[38:39], 4, v[0:1]
	global_store_dwordx4 v[0:1], v[16:19], off
	s_or_b64 exec, exec, s[4:5]
	s_and_saveexec_b64 s[4:5], s[26:27]
	s_cbranch_execnz .LBB0_48

.LBB0_44:
	v_cndmask_b32_e64 v28, v51, v52, s[8:9]
	v_lshl_add_u64 v[0:1], s[66:67], 0, v[28:29]
	v_lshl_add_u64 v[0:1], v[32:33], 4, v[0:1]
	global_store_dwordx4 v[0:1], v[4:7], off
	s_or_b64 exec, exec, s[4:5]
	s_and_saveexec_b64 s[4:5], s[14:15]
	s_cbranch_execnz .LBB0_39

.LBB0_46:
	v_cndmask_b32_e64 v28, v51, v52, s[16:17]
	v_lshl_add_u64 v[0:1], s[66:67], 0, v[28:29]
	v_lshl_add_u64 v[0:1], v[36:37], 4, v[0:1]
	global_store_dwordx4 v[0:1], v[12:15], off
	s_or_b64 exec, exec, s[4:5]
	s_and_saveexec_b64 s[4:5], s[22:23]
	s_cbranch_execnz .LBB0_41

.LBB0_48:
	v_cndmask_b32_e64 v28, v51, v52, s[24:25]
	v_lshl_add_u64 v[0:1], s[66:67], 0, v[28:29]
	v_lshl_add_u64 v[0:1], v[40:41], 4, v[0:1]
	global_store_dwordx4 v[0:1], v[20:23], off
	s_or_b64 exec, exec, s[4:5]
	s_and_saveexec_b64 s[4:5], s[30:31]
	s_cbranch_execz .LBB0_35
.LBB0_49:
	v_cndmask_b32_e64 v28, v51, v52, s[28:29]
	v_lshl_add_u64 v[0:1], s[66:67], 0, v[28:29]
	v_lshl_add_u64 v[0:1], v[42:43], 4, v[0:1]
	s_waitcnt vmcnt(1)
	global_store_dwordx4 v[0:1], v[24:27], off
	s_branch .LBB0_35

.Lb1_nops:
	s_add_i32 s1, s0, 0x18000
	v_mov_b32_e32 v108, s1
	v_min_u32_e32 v101, 0x1feff, v108
	v_add_u32_e32 v108, 0x700, v108
	v_mul_hi_u32 v102, v101, v107
	v_mul_u32_u24_e32 v103, 0x1ff0, v102
	v_and_b32_e32 v104, 7, v102
	v_sub_u32_e32 v103, v101, v103
	v_lshlrev_b32_e32 v104, 23, v104
	v_lshl_add_u32 v103, v103, 10, v104
	v_add_u32_e32 v103, v103, v106
	v_add_u32_e32 v110, 0xa05e000, v103
	v_add_u32_e32 v103, 0x4000, v103
	global_load_dwordx4 v[170:173], v103, s[50:51] nt
	v_min_u32_e32 v101, 0x1feff, v108
	v_add_u32_e32 v108, 0x700, v108
	v_mul_hi_u32 v102, v101, v107
	v_mul_u32_u24_e32 v103, 0x1ff0, v102
	v_and_b32_e32 v104, 7, v102
	v_sub_u32_e32 v103, v101, v103
	v_lshlrev_b32_e32 v104, 23, v104
	v_lshl_add_u32 v103, v103, 10, v104
	v_add_u32_e32 v103, v103, v106
	v_add_u32_e32 v111, 0xa05e000, v103
	v_add_u32_e32 v103, 0x4000, v103
	global_load_dwordx4 v[174:177], v103, s[50:51] nt
	v_min_u32_e32 v101, 0x1feff, v108
	v_add_u32_e32 v108, 0x700, v108
	v_mul_hi_u32 v102, v101, v107
	v_mul_u32_u24_e32 v103, 0x1ff0, v102
	v_and_b32_e32 v104, 7, v102
	v_sub_u32_e32 v103, v101, v103
	v_lshlrev_b32_e32 v104, 23, v104
	v_lshl_add_u32 v103, v103, 10, v104
	v_add_u32_e32 v103, v103, v106
	v_add_u32_e32 v112, 0xa05e000, v103
	v_add_u32_e32 v103, 0x4000, v103
	global_load_dwordx4 v[178:181], v103, s[50:51] nt
	v_min_u32_e32 v101, 0x1feff, v108
	v_add_u32_e32 v108, 0x700, v108
	v_mul_hi_u32 v102, v101, v107
	v_mul_u32_u24_e32 v103, 0x1ff0, v102
	v_and_b32_e32 v104, 7, v102
	v_sub_u32_e32 v103, v101, v103
	v_lshlrev_b32_e32 v104, 23, v104
	v_lshl_add_u32 v103, v103, 10, v104
	v_add_u32_e32 v103, v103, v106
	v_add_u32_e32 v113, 0xa05e000, v103
	v_add_u32_e32 v103, 0x4000, v103
	global_load_dwordx4 v[182:185], v103, s[50:51] nt
	v_min_u32_e32 v101, 0x1feff, v108
	v_add_u32_e32 v108, 0x700, v108
	v_mul_hi_u32 v102, v101, v107
	v_mul_u32_u24_e32 v103, 0x1ff0, v102
	v_and_b32_e32 v104, 7, v102
	v_sub_u32_e32 v103, v101, v103
	v_lshlrev_b32_e32 v104, 23, v104
	v_lshl_add_u32 v103, v103, 10, v104
	v_add_u32_e32 v103, v103, v106
	v_add_u32_e32 v114, 0xa05e000, v103
	v_add_u32_e32 v103, 0x4000, v103
	global_load_dwordx4 v[186:189], v103, s[50:51] nt
	v_min_u32_e32 v101, 0x1feff, v108
	v_add_u32_e32 v108, 0x700, v108
	v_mul_hi_u32 v102, v101, v107
	v_mul_u32_u24_e32 v103, 0x1ff0, v102
	v_and_b32_e32 v104, 7, v102
	v_sub_u32_e32 v103, v101, v103
	v_lshlrev_b32_e32 v104, 23, v104
	v_lshl_add_u32 v103, v103, 10, v104
	v_add_u32_e32 v103, v103, v106
	v_add_u32_e32 v115, 0xa05e000, v103
	v_add_u32_e32 v103, 0x4000, v103
	global_load_dwordx4 v[190:193], v103, s[50:51] nt
	v_min_u32_e32 v101, 0x1feff, v108
	v_add_u32_e32 v108, 0x700, v108
	v_mul_hi_u32 v102, v101, v107
	v_mul_u32_u24_e32 v103, 0x1ff0, v102
	v_and_b32_e32 v104, 7, v102
	v_sub_u32_e32 v103, v101, v103
	v_lshlrev_b32_e32 v104, 23, v104
	v_lshl_add_u32 v103, v103, 10, v104
	v_add_u32_e32 v103, v103, v106
	v_add_u32_e32 v116, 0xa05e000, v103
	v_add_u32_e32 v103, 0x4000, v103
	global_load_dwordx4 v[194:197], v103, s[50:51] nt
	v_min_u32_e32 v101, 0x1feff, v108
	v_add_u32_e32 v108, 0x700, v108
	v_mul_hi_u32 v102, v101, v107
	v_mul_u32_u24_e32 v103, 0x1ff0, v102
	v_and_b32_e32 v104, 7, v102
	v_sub_u32_e32 v103, v101, v103
	v_lshlrev_b32_e32 v104, 23, v104
	v_lshl_add_u32 v103, v103, 10, v104
	v_add_u32_e32 v103, v103, v106
	v_add_u32_e32 v117, 0xa05e000, v103
	v_add_u32_e32 v103, 0x4000, v103
	global_load_dwordx4 v[198:201], v103, s[50:51] nt
	v_min_u32_e32 v101, 0x1feff, v108
	v_add_u32_e32 v108, 0x700, v108
	v_mul_hi_u32 v102, v101, v107
	v_mul_u32_u24_e32 v103, 0x1ff0, v102
	v_and_b32_e32 v104, 7, v102
	v_sub_u32_e32 v103, v101, v103
	v_lshlrev_b32_e32 v104, 23, v104
	v_lshl_add_u32 v103, v103, 10, v104
	v_add_u32_e32 v103, v103, v106
	v_add_u32_e32 v118, 0xa05e000, v103
	v_add_u32_e32 v103, 0x4000, v103
	global_load_dwordx4 v[202:205], v103, s[50:51] nt
	v_min_u32_e32 v101, 0x1feff, v108
	v_add_u32_e32 v108, 0x700, v108
	v_mul_hi_u32 v102, v101, v107
	v_mul_u32_u24_e32 v103, 0x1ff0, v102
	v_and_b32_e32 v104, 7, v102
	v_sub_u32_e32 v103, v101, v103
	v_lshlrev_b32_e32 v104, 23, v104
	v_lshl_add_u32 v103, v103, 10, v104
	v_add_u32_e32 v103, v103, v106
	v_add_u32_e32 v119, 0xa05e000, v103
	v_add_u32_e32 v103, 0x4000, v103
	global_load_dwordx4 v[206:209], v103, s[50:51] nt
	v_min_u32_e32 v101, 0x1feff, v108
	v_add_u32_e32 v108, 0x700, v108
	v_mul_hi_u32 v102, v101, v107
	v_mul_u32_u24_e32 v103, 0x1ff0, v102
	v_and_b32_e32 v104, 7, v102
	v_sub_u32_e32 v103, v101, v103
	v_lshlrev_b32_e32 v104, 23, v104
	v_lshl_add_u32 v103, v103, 10, v104
	v_add_u32_e32 v103, v103, v106
	v_add_u32_e32 v120, 0xa05e000, v103
	v_add_u32_e32 v103, 0x4000, v103
	global_load_dwordx4 v[210:213], v103, s[50:51] nt
	v_min_u32_e32 v101, 0x1feff, v108
	v_add_u32_e32 v108, 0x700, v108
	v_mul_hi_u32 v102, v101, v107
	v_mul_u32_u24_e32 v103, 0x1ff0, v102
	v_and_b32_e32 v104, 7, v102
	v_sub_u32_e32 v103, v101, v103
	v_lshlrev_b32_e32 v104, 23, v104
	v_lshl_add_u32 v103, v103, 10, v104
	v_add_u32_e32 v103, v103, v106
	v_add_u32_e32 v121, 0xa05e000, v103
	v_add_u32_e32 v103, 0x4000, v103
	global_load_dwordx4 v[214:217], v103, s[50:51] nt
	v_min_u32_e32 v101, 0x1feff, v108
	v_add_u32_e32 v108, 0x700, v108
	v_mul_hi_u32 v102, v101, v107
	v_mul_u32_u24_e32 v103, 0x1ff0, v102
	v_and_b32_e32 v104, 7, v102
	v_sub_u32_e32 v103, v101, v103
	v_lshlrev_b32_e32 v104, 23, v104
	v_lshl_add_u32 v103, v103, 10, v104
	v_add_u32_e32 v103, v103, v106
	v_add_u32_e32 v122, 0xa05e000, v103
	v_add_u32_e32 v103, 0x4000, v103
	global_load_dwordx4 v[218:221], v103, s[50:51] nt
	v_min_u32_e32 v101, 0x1feff, v108
	v_add_u32_e32 v108, 0x700, v108
	v_mul_hi_u32 v102, v101, v107
	v_mul_u32_u24_e32 v103, 0x1ff0, v102
	v_and_b32_e32 v104, 7, v102
	v_sub_u32_e32 v103, v101, v103
	v_lshlrev_b32_e32 v104, 23, v104
	v_lshl_add_u32 v103, v103, 10, v104
	v_add_u32_e32 v103, v103, v106
	v_add_u32_e32 v123, 0xa05e000, v103
	v_add_u32_e32 v103, 0x4000, v103
	global_load_dwordx4 v[222:225], v103, s[50:51] nt
	v_min_u32_e32 v101, 0x1feff, v108
	v_add_u32_e32 v108, 0x700, v108
	v_mul_hi_u32 v102, v101, v107
	v_mul_u32_u24_e32 v103, 0x1ff0, v102
	v_and_b32_e32 v104, 7, v102
	v_sub_u32_e32 v103, v101, v103
	v_lshlrev_b32_e32 v104, 23, v104
	v_lshl_add_u32 v103, v103, 10, v104
	v_add_u32_e32 v103, v103, v106
	v_add_u32_e32 v124, 0xa05e000, v103
	v_add_u32_e32 v103, 0x4000, v103
	global_load_dwordx4 v[226:229], v103, s[50:51] nt
	v_min_u32_e32 v101, 0x1feff, v108
	v_add_u32_e32 v108, 0x700, v108
	v_mul_hi_u32 v102, v101, v107
	v_mul_u32_u24_e32 v103, 0x1ff0, v102
	v_and_b32_e32 v104, 7, v102
	v_sub_u32_e32 v103, v101, v103
	v_lshlrev_b32_e32 v104, 23, v104
	v_lshl_add_u32 v103, v103, 10, v104
	v_add_u32_e32 v103, v103, v106
	v_add_u32_e32 v125, 0xa05e000, v103
	v_add_u32_e32 v103, 0x4000, v103
	global_load_dwordx4 v[230:233], v103, s[50:51] nt
	v_min_u32_e32 v101, 0x1feff, v108
	v_add_u32_e32 v108, 0x700, v108
	v_mul_hi_u32 v102, v101, v107
	v_mul_u32_u24_e32 v103, 0x1ff0, v102
	v_and_b32_e32 v104, 7, v102
	v_sub_u32_e32 v103, v101, v103
	v_lshlrev_b32_e32 v104, 23, v104
	v_lshl_add_u32 v103, v103, 10, v104
	v_add_u32_e32 v103, v103, v106
	v_add_u32_e32 v126, 0xa05e000, v103
	v_add_u32_e32 v103, 0x4000, v103
	global_load_dwordx4 v[234:237], v103, s[50:51] nt
	v_min_u32_e32 v101, 0x1feff, v108
	v_add_u32_e32 v108, 0x700, v108
	v_mul_hi_u32 v102, v101, v107
	v_mul_u32_u24_e32 v103, 0x1ff0, v102
	v_and_b32_e32 v104, 7, v102
	v_sub_u32_e32 v103, v101, v103
	v_lshlrev_b32_e32 v104, 23, v104
	v_lshl_add_u32 v103, v103, 10, v104
	v_add_u32_e32 v103, v103, v106
	v_add_u32_e32 v127, 0xa05e000, v103
	v_add_u32_e32 v103, 0x4000, v103
	global_load_dwordx4 v[140:143], v103, s[50:51] nt
	v_min_u32_e32 v101, 0x1feff, v108
	v_add_u32_e32 v108, 0x700, v108
	v_mul_hi_u32 v102, v101, v107
	v_mul_u32_u24_e32 v103, 0x1ff0, v102
	v_and_b32_e32 v104, 7, v102
	v_sub_u32_e32 v103, v101, v103
	v_lshlrev_b32_e32 v104, 23, v104
	v_lshl_add_u32 v103, v103, 10, v104
	v_add_u32_e32 v103, v103, v106
	v_add_u32_e32 v128, 0xa05e000, v103
	v_add_u32_e32 v103, 0x4000, v103
	global_load_dwordx4 v[144:147], v103, s[50:51] nt
	s_waitcnt vmcnt(18)
	global_store_dwordx4 v110, v[170:173], s[66:67]
	s_waitcnt vmcnt(18)
	global_store_dwordx4 v111, v[174:177], s[66:67]
	s_waitcnt vmcnt(18)
	global_store_dwordx4 v112, v[178:181], s[66:67]
	s_waitcnt vmcnt(18)
	global_store_dwordx4 v113, v[182:185], s[66:67]
	s_waitcnt vmcnt(18)
	global_store_dwordx4 v114, v[186:189], s[66:67]
	s_waitcnt vmcnt(18)
	global_store_dwordx4 v115, v[190:193], s[66:67]
	s_waitcnt vmcnt(18)
	global_store_dwordx4 v116, v[194:197], s[66:67]
	s_waitcnt vmcnt(18)
	global_store_dwordx4 v117, v[198:201], s[66:67]
	s_waitcnt vmcnt(18)
	global_store_dwordx4 v118, v[202:205], s[66:67]
	s_waitcnt vmcnt(18)
	global_store_dwordx4 v119, v[206:209], s[66:67]
	s_waitcnt vmcnt(18)
	global_store_dwordx4 v120, v[210:213], s[66:67]
	s_waitcnt vmcnt(18)
	global_store_dwordx4 v121, v[214:217], s[66:67]
	s_waitcnt vmcnt(18)
	global_store_dwordx4 v122, v[218:221], s[66:67]
	s_waitcnt vmcnt(18)
	global_store_dwordx4 v123, v[222:225], s[66:67]
	s_waitcnt vmcnt(18)
	global_store_dwordx4 v124, v[226:229], s[66:67]
	s_waitcnt vmcnt(18)
	global_store_dwordx4 v125, v[230:233], s[66:67]
	s_waitcnt vmcnt(18)
	global_store_dwordx4 v126, v[234:237], s[66:67]
	s_waitcnt vmcnt(18)
	global_store_dwordx4 v127, v[140:143], s[66:67]
	s_waitcnt vmcnt(18)
	global_store_dwordx4 v128, v[144:147], s[66:67]
	s_cmpk_lt_u32 s0, 0x160
	s_cbranch_scc0 .Lb1_skip
	global_store_dwordx4 v99, v[92:95], s[66:67]

.LBB0_344:
	s_or_b32 s14, s0, s73
	s_or_b32 s0, s0, s87
	s_add_i32 s0, s0, s85
	s_lshl_b32 s12, s0, 9
	s_cmpk_gt_i32 s0, 0x1fef
	s_cselect_b64 s[18:19], -1, 0
	s_add_i32 s13, s12, 0xffc02000
	s_and_b64 s[0:1], s[18:19], exec
	s_cselect_b32 s15, s13, s12
	s_mul_hi_i32 s0, s15, 0x80402011
	s_add_i32 s0, s0, s15
	s_lshr_b32 s1, s0, 31
	s_ashr_i32 s0, s0, 18
	s_add_i32 s16, s0, s1
	s_add_i32 s17, s16, 1
	s_and_b64 s[12:13], s[18:19], exec
	v_mbcnt_lo_u32_b32 v172, -1, 0
	v_mbcnt_hi_u32_b32 v172, -1, v172
	s_cselect_b32 s12, s51, s49
	s_cselect_b32 s13, s50, s48
	s_and_b32 s1, s14, s88
	s_lshr_b32 s14, s14, s87
	v_ashrrev_i32_e32 v36, 3, v172
	s_or_b32 s1, s1, s84
	s_lshl_b32 s14, s14, s89
	v_subrev_u32_e32 v37, 64, v36
	s_add_i32 s1, s1, s14
	v_lshlrev_b32_e32 v37, s87, v37
	v_lshlrev_b32_e32 v1, 4, v172
	v_add_u32_e32 v37, s1, v37
	v_and_b32_e32 v41, 0x70, v1
	v_max_i32_e32 v37, 0, v37
	v_lshl_or_b32 v163, v37, 7, v41
	v_subrev_u32_e32 v37, 56, v36
	v_lshlrev_b32_e32 v37, s87, v37
	v_add_u32_e32 v37, s1, v37
	v_max_i32_e32 v37, 0, v37
	v_lshl_or_b32 v165, v37, 7, v41
	v_subrev_u32_e32 v37, 48, v36
	v_lshlrev_b32_e32 v37, s87, v37
	v_add_u32_e32 v37, s1, v37
	v_max_i32_e32 v37, 0, v37
	v_lshl_or_b32 v167, v37, 7, v41
	v_subrev_u32_e32 v37, 40, v36
	v_lshlrev_b32_e32 v37, s87, v37
	v_add_u32_e32 v37, s1, v37
	v_max_i32_e32 v37, 0, v37
	v_lshl_or_b32 v186, v37, 7, v41
	v_subrev_u32_e32 v37, 32, v36
	v_lshlrev_b32_e32 v37, s87, v37
	v_add_u32_e32 v37, s1, v37
	v_max_i32_e32 v37, 0, v37
	v_lshl_or_b32 v144, v37, 7, v41
	v_subrev_u32_e32 v37, 24, v36
	v_lshlrev_b32_e32 v37, s87, v37
	v_add_u32_e32 v37, s1, v37
	v_max_i32_e32 v37, 0, v37
	v_lshl_or_b32 v154, v37, 7, v41
	v_add_lshl_u32 v37, v36, -16, s87
	v_add_u32_e32 v37, s1, v37
	v_max_i32_e32 v37, 0, v37
	v_lshl_or_b32 v156, v37, 7, v41
	v_add_lshl_u32 v37, v36, -8, s87
	v_add_u32_e32 v37, s1, v37
	v_max_i32_e32 v37, 0, v37
	v_lshl_or_b32 v158, v37, 7, v41
	v_lshlrev_b32_e32 v37, s87, v36
	v_add_u32_e32 v37, s1, v37
	v_max_i32_e32 v37, 0, v37
	v_lshl_or_b32 v160, v37, 7, v41
	v_add_lshl_u32 v37, v36, 8, s87
	v_add_u32_e32 v37, s1, v37
	v_max_i32_e32 v37, 0, v37
	v_lshl_or_b32 v162, v37, 7, v41
	v_add_lshl_u32 v37, v36, 16, s87
	v_add_u32_e32 v37, s1, v37
	v_and_b32_e32 v176, 31, v172
	v_max_i32_e32 v37, 0, v37
	v_lshlrev_b32_e32 v0, s87, v176
	v_lshl_or_b32 v164, v37, 7, v41
	v_add_lshl_u32 v37, v36, 24, s87
	s_mul_i32 s0, s17, 0x7fc00
	v_add_u32_e32 v174, s1, v0
	v_add_u32_e32 v37, s1, v37
	v_add_u32_e32 v187, s15, v172
	v_ashrrev_i32_e32 v173, 5, v172
	v_add_u32_e32 v0, s34, v174
	v_max_i32_e32 v37, 0, v37
	v_mov_b32_e32 v188, s17
	v_mov_b32_e32 v189, s16
	v_cmp_gt_i32_e32 vcc, s0, v187
	v_mul_lo_u32 v0, v0, s75
	v_lshlrev_b32_e32 v40, 4, v173
	v_lshl_or_b32 v166, v37, 7, v41
	v_cndmask_b32_e32 v37, v188, v189, vcc
	v_lshlrev_b32_e32 v38, 4, v187
	v_add3_u32 v0, v40, s10, v0
	v_lshl_add_u32 v190, v37, 14, v38
	v_add_u32_e32 v37, 64, v187
	v_add_u32_e32 v0, 0xffffff80, v36
	v_add_u32_e32 v8, 0xffffff90, v36
	v_add_u32_e32 v20, 0xffffffa0, v36
	v_add_u32_e32 v28, 0xffffffb0, v36
	v_cmp_gt_i32_e32 vcc, s0, v37
	v_lshlrev_b32_e32 v0, s87, v0
	v_lshlrev_b32_e32 v8, s87, v8
	v_lshlrev_b32_e32 v20, s87, v20
	v_lshlrev_b32_e32 v28, s87, v28
	v_cndmask_b32_e32 v38, v188, v189, vcc
	v_lshlrev_b32_e32 v37, 4, v37
	v_add_u32_e32 v0, s1, v0
	v_add_u32_e32 v8, s1, v8
	v_add_u32_e32 v20, s1, v20
	v_add_u32_e32 v28, s1, v28
	v_lshl_add_u32 v191, v38, 14, v37
	v_add_u32_e32 v37, 0x80, v187
	v_max_i32_e32 v0, 0, v0
	v_max_i32_e32 v8, 0, v8
	v_max_i32_e32 v20, 0, v20
	v_max_i32_e32 v28, 0, v28
	v_cmp_gt_i32_e32 vcc, s0, v37
	v_lshl_or_b32 v124, v0, 7, v41
	v_add_u32_e32 v0, 0xffffff88, v36
	v_lshl_or_b32 v126, v8, 7, v41
	v_add_u32_e32 v8, 0xffffff98, v36
	v_lshl_or_b32 v155, v20, 7, v41
	v_add_u32_e32 v20, 0xffffffa8, v36
	v_lshl_or_b32 v159, v28, 7, v41
	v_add_u32_e32 v28, 0xffffffb8, v36
	v_cndmask_b32_e32 v38, v188, v189, vcc
	v_lshlrev_b32_e32 v37, 4, v37
	v_lshlrev_b32_e32 v0, s87, v0
	v_lshlrev_b32_e32 v8, s87, v8
	v_lshlrev_b32_e32 v20, s87, v20
	v_lshlrev_b32_e32 v28, s87, v28
	v_lshl_add_u32 v192, v38, 14, v37
	v_add_u32_e32 v37, 0xc0, v187
	s_add_u32 s36, s13, 0x4000
	v_add_u32_e32 v0, s1, v0
	v_add_u32_e32 v8, s1, v8
	v_add_u32_e32 v20, s1, v20
	v_add_u32_e32 v28, s1, v28
	v_cmp_gt_i32_e32 vcc, s0, v37
	s_addc_u32 s37, s12, 0
	v_max_i32_e32 v0, 0, v0
	v_max_i32_e32 v8, 0, v8
	v_max_i32_e32 v20, 0, v20
	v_max_i32_e32 v28, 0, v28
	v_cndmask_b32_e32 v38, v188, v189, vcc
	v_lshlrev_b32_e32 v37, 4, v37
	v_lshl_or_b32 v125, v0, 7, v41
	global_load_dwordx4 v[0:3], v124, s[40:41]
	global_load_dwordx4 v[4:7], v125, s[40:41]
	v_lshl_or_b32 v127, v8, 7, v41
	global_load_dwordx4 v[8:11], v126, s[40:41]
	global_load_dwordx4 v[12:15], v127, s[40:41]
	v_lshl_or_b32 v157, v20, 7, v41
	global_load_dwordx4 v[20:23], v155, s[40:41]
	global_load_dwordx4 v[24:27], v157, s[40:41]
	v_lshl_or_b32 v161, v28, 7, v41
	global_load_dwordx4 v[28:31], v159, s[40:41]
	global_load_dwordx4 v[32:35], v161, s[40:41]
	global_load_dwordx4 v[48:51], v163, s[40:41]
	global_load_dwordx4 v[52:55], v165, s[40:41]
	global_load_dwordx4 v[56:59], v167, s[40:41]
	global_load_dwordx4 v[60:63], v186, s[40:41]
	global_load_dwordx4 v[92:95], v154, s[40:41]
	global_load_dwordx4 v[96:99], v156, s[40:41]
	global_load_dwordx4 v[100:103], v158, s[40:41]
	global_load_dwordx4 v[104:107], v160, s[40:41]
	global_load_dwordx4 v[108:111], v162, s[40:41]
	global_load_dwordx4 v[112:115], v164, s[40:41]
	global_load_dwordx4 v[116:119], v144, s[40:41]
	global_load_dwordx4 v[120:123], v166, s[40:41]
	global_load_dwordx4 v[146:149], v190, s[36:37] nt
	global_load_dwordx4 v[150:153], v191, s[36:37] nt
	v_lshl_add_u32 v193, v38, 14, v37
	global_load_dwordx4 v[178:181], v192, s[36:37] nt
	global_load_dwordx4 v[182:185], v193, s[36:37] nt
	s_and_b64 s[12:13], s[18:19], exec
	s_mov_b32 s12, 0xa05e000
	s_cselect_b32 s12, s12, 0x605e000
	s_add_u32 s18, s66, s12
	v_lshlrev_b32_e32 v177, 2, v173
	s_addc_u32 s19, s67, 0
	v_mul_lo_u32 v43, v36, s76
	v_add_u32_e32 v168, s72, v41
	v_add_u32_e32 v44, 0x480, v43
	v_add_u32_e32 v45, 0x900, v43
	v_add_u32_e32 v46, 0xd80, v43
	v_mul_u32_u24_e32 v42, 0x90, v176
	v_add_u32_e32 v175, v168, v43
	v_add_u32_e32 v128, v168, v44
	v_add_u32_e32 v129, v168, v45
	v_add_u32_e32 v130, v168, v46
	s_waitcnt vmcnt(23)
	ds_write_b128 v175, v[0:3]
	s_waitcnt vmcnt(22)
	ds_write_b128 v128, v[4:7]
	s_waitcnt vmcnt(21)
	ds_write_b128 v129, v[8:11]
	s_waitcnt vmcnt(20)
	ds_write_b128 v130, v[12:15]
	v_add3_u32 v131, s72, v42, v40
	ds_read_b128 v[0:3], v131
	ds_read_b128 v[36:39], v131 offset:32
	s_waitcnt lgkmcnt(1)
	v_mfma_f32_32x32x16_bf16 v[0:15], v[0:3], v[240:243], 0
	v_add_u32_e32 v47, s74, v41
	v_add_u32_e32 v132, v47, v43
	v_add3_u32 v133, s74, v42, v40
	ds_read_b128 v[40:43], v131 offset:96
	v_add_u32_e32 v134, v47, v44
	v_add_u32_e32 v135, v47, v45
	v_add_u32_e32 v136, v47, v46
	s_waitcnt lgkmcnt(1)
	v_mfma_f32_32x32x16_bf16 v[0:15], v[36:39], v[244:247], v[0:15]
	ds_read_b128 v[36:39], v131 offset:64
	s_waitcnt vmcnt(19)
	ds_write_b128 v132, v[20:23]
	s_waitcnt vmcnt(18)
	ds_write_b128 v134, v[24:27]
	s_waitcnt vmcnt(17)
	ds_write_b128 v135, v[28:31]
	s_waitcnt vmcnt(16)
	ds_write_b128 v136, v[32:35]
	ds_read_b128 v[20:23], v133
	s_waitcnt lgkmcnt(5)
	v_mfma_f32_32x32x16_bf16 v[0:15], v[36:39], v[248:251], v[0:15]
	v_mfma_f32_32x32x16_bf16 v[0:15], v[40:43], v[252:255], v[0:15]
	s_waitcnt lgkmcnt(0)
	v_mfma_f32_32x32x16_bf16 v[32:47], v[20:23], v[240:243], 0
	ds_read_b128 v[20:23], v133 offset:32
	s_waitcnt lgkmcnt(0)
	v_mfma_f32_32x32x16_bf16 v[32:47], v[20:23], v[244:247], v[32:47]
	ds_read_b128 v[20:23], v133 offset:64
	s_waitcnt lgkmcnt(0)
	v_mfma_f32_32x32x16_bf16 v[32:47], v[20:23], v[248:251], v[32:47]
	ds_read_b128 v[20:23], v133 offset:96
	s_waitcnt vmcnt(15)
	ds_write_b128 v175, v[48:51]
	s_waitcnt vmcnt(14)
	ds_write_b128 v128, v[52:55]
	s_waitcnt vmcnt(13)
	ds_write_b128 v129, v[56:59]
	s_waitcnt vmcnt(12)
	ds_write_b128 v130, v[60:63]
	s_waitcnt lgkmcnt(4)
	v_mfma_f32_32x32x16_bf16 v[32:47], v[20:23], v[252:255], v[32:47]
	ds_read_b128 v[20:23], v131
	s_waitcnt lgkmcnt(0)
	v_mfma_f32_32x32x16_bf16 v[64:79], v[20:23], v[240:243], 0
	ds_read_b128 v[20:23], v131 offset:32
	s_waitcnt lgkmcnt(0)
	v_mfma_f32_32x32x16_bf16 v[64:79], v[20:23], v[244:247], v[64:79]
	ds_read_b128 v[20:23], v131 offset:64
	s_waitcnt lgkmcnt(0)
	v_mfma_f32_32x32x16_bf16 v[64:79], v[20:23], v[248:251], v[64:79]
	ds_read_b128 v[20:23], v131 offset:96
	s_waitcnt vmcnt(5)
	ds_write_b128 v132, v[116:119]
	ds_write_b128 v134, v[92:95]
	ds_write_b128 v135, v[96:99]
	ds_write_b128 v136, v[100:103]
	s_waitcnt lgkmcnt(4)
	v_mfma_f32_32x32x16_bf16 v[64:79], v[20:23], v[252:255], v[64:79]
	ds_read_b128 v[20:23], v133
	s_waitcnt lgkmcnt(0)
	v_mfma_f32_32x32x16_bf16 v[48:63], v[20:23], v[240:243], 0
	ds_read_b128 v[20:23], v133 offset:32
	s_waitcnt lgkmcnt(0)
	v_mfma_f32_32x32x16_bf16 v[48:63], v[20:23], v[244:247], v[48:63]
	ds_read_b128 v[20:23], v133 offset:64
	s_waitcnt lgkmcnt(0)
	v_mfma_f32_32x32x16_bf16 v[48:63], v[20:23], v[248:251], v[48:63]
	ds_read_b128 v[20:23], v133 offset:96
	ds_write_b128 v175, v[104:107]
	ds_write_b128 v128, v[108:111]
	ds_write_b128 v129, v[112:115]
	s_waitcnt vmcnt(4)
	ds_write_b128 v130, v[120:123]
	ds_read_b128 v[92:95], v131 offset:32
	s_waitcnt lgkmcnt(5)
	v_mfma_f32_32x32x16_bf16 v[48:63], v[20:23], v[252:255], v[48:63]
	ds_read_b128 v[20:23], v131
	s_waitcnt lgkmcnt(0)
	v_mfma_f32_32x32x16_bf16 v[16:31], v[20:23], v[240:243], 0
	v_mfma_f32_32x32x16_bf16 v[16:31], v[92:95], v[244:247], v[16:31]
	ds_read_b128 v[88:91], v131 offset:64
	s_waitcnt lgkmcnt(0)
	v_mfma_f32_32x32x16_bf16 v[16:31], v[88:91], v[248:251], v[16:31]
	ds_read_b128 v[84:87], v131 offset:96
	s_waitcnt lgkmcnt(0)
	v_mfma_f32_32x32x16_bf16 v[16:31], v[84:87], v[252:255], v[16:31]
	global_load_dwordx4 v[140:143], v124, s[42:43]
	global_load_dwordx4 v[136:139], v125, s[42:43]
	global_load_dwordx4 v[132:135], v126, s[42:43]
	global_load_dwordx4 v[128:131], v127, s[42:43]
	global_load_dwordx4 v[112:115], v155, s[42:43]
	global_load_dwordx4 v[116:119], v157, s[42:43]
	global_load_dwordx4 v[120:123], v159, s[42:43]
	s_nop 0
	global_load_dwordx4 v[124:127], v161, s[42:43]
	global_load_dwordx4 v[96:99], v163, s[42:43]
	global_load_dwordx4 v[100:103], v165, s[42:43]
	global_load_dwordx4 v[104:107], v167, s[42:43]
	global_load_dwordx4 v[108:111], v186, s[42:43]
	v_add_u32_e32 v80, 0x100, v187
	v_cmp_gt_i32_e32 vcc, s0, v80
	v_lshlrev_b32_e32 v80, 4, v80
	s_waitcnt vmcnt(15)
	global_store_dwordx4 v190, v[146:149], s[18:19]
	s_waitcnt vmcnt(15)
	global_store_dwordx4 v191, v[150:153], s[18:19]
	s_waitcnt vmcnt(15)
	global_store_dwordx4 v192, v[178:181], s[18:19]
	s_waitcnt vmcnt(15)
	global_store_dwordx4 v193, v[182:185], s[18:19]
	v_cndmask_b32_e32 v81, v188, v189, vcc
	v_lshl_add_u32 v146, v81, 14, v80
	v_add_u32_e32 v80, 0x140, v187
	v_cmp_gt_i32_e32 vcc, s0, v80
	v_add_u32_e32 v88, 0x180, v187
	v_lshlrev_b32_e32 v80, 4, v80
	v_cndmask_b32_e32 v81, v188, v189, vcc
	v_cmp_gt_i32_e32 vcc, s0, v88
	v_lshlrev_b32_e32 v88, 4, v88
	v_lshl_add_u32 v148, v81, 14, v80
	v_cndmask_b32_e32 v89, v188, v189, vcc
	v_lshl_add_u32 v150, v89, 14, v88
	v_add_u32_e32 v88, 0x1c0, v187
	v_cmp_gt_i32_e32 vcc, s0, v88
	v_lshlrev_b32_e32 v88, 4, v88
	global_load_dwordx4 v[84:87], v146, s[36:37] nt
	global_load_dwordx4 v[80:83], v148, s[36:37] nt
	v_cndmask_b32_e32 v89, v188, v189, vcc
	v_lshl_add_u32 v152, v89, 14, v88
	global_load_dwordx4 v[92:95], v150, s[36:37] nt
	global_load_dwordx4 v[88:91], v152, s[36:37] nt
	s_add_i32 s13, s86, 1
	s_cmp_lg_u32 s56, 0
	s_cselect_b32 s12, s86, s13
	s_cselect_b32 s14, 1, 0
	s_min_i32 s12, s12, 2
	s_lshl_b32 s13, s12, 1
	s_or_b32 s14, s14, s73
	s_lshl_b32 s15, -1, s13
	s_andn2_b32 s15, s14, s15
	s_or_b32 s15, s15, s84
	s_lshr_b32 s14, s14, s13
	s_add_i32 s17, s13, 5
	s_lshl_b32 s14, s14, s17
	s_add_i32 s15, s15, s14
	s_add_i32 s15, s15, s34
	v_lshlrev_b32_e32 v194, s13, v176
	v_add_u32_e32 v194, s15, v194
	v_mul_lo_u32 v194, v194, s75
	v_lshlrev_b32_e32 v195, 4, v173
	v_add3_u32 v194, v195, s10, v194
	global_load_dwordx4 v[240:243], v194, s[28:29]
	global_load_dwordx4 v[244:247], v194, s[28:29] offset:32
	global_load_dwordx4 v[248:251], v194, s[28:29] offset:64
	global_load_dwordx4 v[252:255], v194, s[28:29] offset:96
	s_ashr_i32 s0, s1, s87
	s_sub_i32 s1, 0x80, s0
	v_max_i32_e32 v147, s1, v176
	v_sub_u32_e32 v147, v147, v177
	v_cmp_gt_i32_e32 vcc, 1, v147
	s_sub_i32 s1, 0x7f, s0
	s_ashr_i32 s1, s1, 5
	v_cndmask_b32_e32 v192, v171, v0, vcc
	v_cmp_gt_i32_e32 vcc, 2, v147
	s_cmpk_lt_i32 s0, 0x80
	s_cselect_b32 s0, s1, -1
	v_cndmask_b32_e32 v190, v171, v1, vcc
	v_cmp_gt_i32_e32 vcc, 3, v147
	s_mov_b32 s1, 0xff800000
	v_max3_f32 v0, v192, s1, v190
	v_cndmask_b32_e32 v193, v171, v2, vcc
	v_cmp_gt_i32_e32 vcc, 4, v147
	s_cmp_lt_i32 s0, 1
	s_mov_b64 s[36:37], -1
	v_cndmask_b32_e32 v191, v171, v3, vcc
	v_cmp_gt_i32_e32 vcc, 9, v147
	v_max3_f32 v0, v0, v193, v191
	s_nop 0
	v_cndmask_b32_e32 v189, v171, v4, vcc
	v_cmp_gt_i32_e32 vcc, 10, v147
	s_nop 1
	v_cndmask_b32_e32 v187, v171, v5, vcc
	v_cmp_gt_i32_e32 vcc, 11, v147
	v_max3_f32 v0, v0, v189, v187
	s_nop 0
	v_cndmask_b32_e32 v188, v171, v6, vcc
	v_cmp_gt_i32_e32 vcc, 12, v147
	s_nop 1
	v_cndmask_b32_e32 v186, v171, v7, vcc
	v_cmp_gt_i32_e32 vcc, 17, v147
	v_max3_f32 v0, v0, v188, v186
	s_nop 0
	v_cndmask_b32_e32 v185, v171, v8, vcc
	v_cmp_gt_i32_e32 vcc, 18, v147
	s_nop 1
	v_cndmask_b32_e32 v183, v171, v9, vcc
	v_cmp_gt_i32_e32 vcc, 19, v147
	v_max3_f32 v0, v0, v185, v183
	s_nop 0
	v_cndmask_b32_e32 v184, v171, v10, vcc
	v_cmp_gt_i32_e32 vcc, 20, v147
	s_nop 1
	v_cndmask_b32_e32 v182, v171, v11, vcc
	v_cmp_gt_i32_e32 vcc, 25, v147
	v_max3_f32 v0, v0, v184, v182
	s_nop 0
	v_cndmask_b32_e32 v181, v171, v12, vcc
	v_cmp_gt_i32_e32 vcc, 26, v147
	s_nop 1
	v_cndmask_b32_e32 v179, v171, v13, vcc
	v_cmp_gt_i32_e32 vcc, 27, v147
	v_max3_f32 v0, v0, v181, v179
	s_nop 0
	v_cndmask_b32_e32 v180, v171, v14, vcc
	v_cmp_gt_i32_e32 vcc, 28, v147
	s_nop 1
	v_cndmask_b32_e32 v178, v171, v15, vcc
	v_max3_f32 v149, v0, v180, v178
	s_cbranch_scc1 .LBB0_346
	v_cmp_gt_i32_e32 vcc, 33, v147
	s_nop 1
	v_cndmask_b32_e32 v0, v171, v32, vcc
	v_cmp_gt_i32_e32 vcc, 34, v147
	s_nop 1
	v_cndmask_b32_e32 v1, v171, v33, vcc
	v_cmp_gt_i32_e32 vcc, 35, v147
	v_max3_f32 v4, v149, v0, v1
	s_nop 0
	v_cndmask_b32_e32 v2, v171, v34, vcc
	v_cmp_gt_i32_e32 vcc, 36, v147
	s_nop 1
	v_cndmask_b32_e32 v3, v171, v35, vcc
	v_cmp_gt_i32_e32 vcc, 41, v147
	v_max3_f32 v6, v4, v2, v3
	s_nop 0
	v_cndmask_b32_e32 v4, v171, v36, vcc
	v_cmp_gt_i32_e32 vcc, 42, v147
	s_nop 1
	v_cndmask_b32_e32 v5, v171, v37, vcc
	v_cmp_gt_i32_e32 vcc, 43, v147
	v_max3_f32 v8, v6, v4, v5
	s_nop 0
	v_cndmask_b32_e32 v6, v171, v38, vcc
	v_cmp_gt_i32_e32 vcc, 44, v147
	s_nop 1
	v_cndmask_b32_e32 v7, v171, v39, vcc
	v_cmp_gt_i32_e32 vcc, 49, v147
	v_max3_f32 v10, v8, v6, v7
	s_nop 0
	v_cndmask_b32_e32 v8, v171, v40, vcc
	v_cmp_gt_i32_e32 vcc, 50, v147
	s_nop 1
	v_cndmask_b32_e32 v9, v171, v41, vcc
	v_cmp_gt_i32_e32 vcc, 51, v147
	v_max3_f32 v12, v10, v8, v9
	s_nop 0
	v_cndmask_b32_e32 v10, v171, v42, vcc
	v_cmp_gt_i32_e32 vcc, 52, v147
	s_nop 1
	v_cndmask_b32_e32 v11, v171, v43, vcc
	v_cmp_gt_i32_e32 vcc, 57, v147
	v_max3_f32 v14, v12, v10, v11
	s_nop 0
	v_cndmask_b32_e32 v12, v171, v44, vcc
	v_cmp_gt_i32_e32 vcc, 58, v147
	s_nop 1
	v_cndmask_b32_e32 v13, v171, v45, vcc
	v_cmp_gt_i32_e32 vcc, 59, v147
	v_max3_f32 v151, v14, v12, v13
	s_nop 0
	v_cndmask_b32_e32 v14, v171, v46, vcc
	v_cmp_gt_i32_e32 vcc, 60, v147
	s_nop 1
	v_cndmask_b32_e32 v15, v171, v47, vcc
	v_max3_f32 v151, v151, v14, v15
	s_cbranch_execnz .LBB0_348
	s_branch .LBB0_347

.LBB0_356:
	v_and_b32_e32 v49, 16, v172
	v_lshlrev_b32_e32 v50, 2, v172
	v_and_or_b32 v49, v50, 12, v49
	v_or_b32_e32 v50, 0x80, v176
	v_sub_u32_e32 v50, v50, v177
	s_movk_i32 s0, 0x7f
	v_cmp_lt_i32_e32 vcc, s0, v50
	s_movk_i32 s0, 0x80
	v_lshrrev_b32_e32 v48, 2, v172
	v_cndmask_b32_e32 v16, v171, v16, vcc
	v_cmp_lt_i32_e32 vcc, s0, v50
	s_movk_i32 s0, 0x81
	v_and_or_b32 v48, v48, 3, v177
	v_cndmask_b32_e32 v17, v171, v17, vcc
	v_cmp_lt_i32_e32 vcc, s0, v50
	s_movk_i32 s0, 0x82
	v_mov_b32_e32 v155, v145
	v_cndmask_b32_e32 v18, v171, v18, vcc
	v_cmp_lt_i32_e32 vcc, s0, v50
	s_movk_i32 s0, 0x87
	v_mov_b32_e32 v157, v145
	v_cndmask_b32_e32 v19, v171, v19, vcc
	v_cmp_lt_i32_e32 vcc, s0, v50
	s_movk_i32 s0, 0x88
	v_mov_b32_e32 v159, v145
	v_cndmask_b32_e32 v20, v171, v20, vcc
	v_cmp_lt_i32_e32 vcc, s0, v50
	s_movk_i32 s0, 0x89
	v_mov_b32_e32 v161, v145
	v_cndmask_b32_e32 v21, v171, v21, vcc
	v_cmp_lt_i32_e32 vcc, s0, v50
	s_movk_i32 s0, 0x8a
	v_mov_b32_e32 v163, v145
	v_cndmask_b32_e32 v22, v171, v22, vcc
	v_cmp_lt_i32_e32 vcc, s0, v50
	s_movk_i32 s0, 0x8f
	v_mov_b32_e32 v165, v145
	v_cndmask_b32_e32 v23, v171, v23, vcc
	v_cmp_lt_i32_e32 vcc, s0, v50
	s_movk_i32 s0, 0x91
	v_mov_b32_e32 v167, v145
	v_cndmask_b32_e32 v24, v171, v24, vcc
	v_cmp_lt_i32_e32 vcc, s76, v50
	v_mov_b32_e32 v147, v145
	v_mov_b32_e32 v149, v145
	v_cndmask_b32_e32 v25, v171, v25, vcc
	v_cmp_lt_i32_e32 vcc, s0, v50
	s_movk_i32 s0, 0x92
	v_mov_b32_e32 v151, v145
	v_cndmask_b32_e32 v26, v171, v26, vcc
	v_cmp_lt_i32_e32 vcc, s0, v50
	s_movk_i32 s0, 0x97
	v_mov_b32_e32 v153, v145
	v_cndmask_b32_e32 v27, v171, v27, vcc
	v_cmp_lt_i32_e32 vcc, s0, v50
	s_movk_i32 s0, 0x98
	v_mul_lo_u32 v48, v48, s76
	v_cndmask_b32_e32 v28, v171, v28, vcc
	v_cmp_lt_i32_e32 vcc, s0, v50
	s_movk_i32 s0, 0x99
	v_lshlrev_b32_e32 v49, 1, v49
	v_cndmask_b32_e32 v29, v171, v29, vcc
	v_cmp_lt_i32_e32 vcc, s0, v50
	s_movk_i32 s0, 0x9a
	s_nop 0
	v_cndmask_b32_e32 v30, v171, v30, vcc
	v_cmp_lt_i32_e32 vcc, s0, v50
	v_max3_f32 v50, v70, v16, v17
	v_max3_f32 v50, v50, v18, v19
	v_max3_f32 v50, v50, v20, v21
	v_max3_f32 v50, v50, v22, v23
	v_max3_f32 v50, v50, v24, v25
	v_max3_f32 v50, v50, v26, v27
	v_cndmask_b32_e32 v31, v171, v31, vcc
	v_max3_f32 v50, v50, v28, v29
	v_max3_f32 v50, v50, v30, v31
	v_mov_b32_e32 v51, v50
	s_nop 1
	v_permlane32_swap_b32_e32 v50, v51
	v_max_f32_e32 v51, v51, v51
	v_max_f32_e32 v50, v50, v50
	v_max_f32_e32 v70, v50, v51
	v_mul_f32_e32 v50, 0x3e38aa3b, v70
	v_fma_f32 v51, v192, s77, -v50
	v_exp_f32_e32 v51, v51
	v_fma_f32 v52, v190, s77, -v50
	v_exp_f32_e32 v52, v52
	v_fma_f32 v53, v193, s77, -v50
	v_exp_f32_e32 v53, v53
	v_fma_f32 v54, v191, s77, -v50
	v_exp_f32_e32 v54, v54
	v_fma_f32 v56, v189, s77, -v50
	v_add_f32_e32 v55, 0, v51
	v_exp_f32_e32 v56, v56
	v_fma_f32 v57, v187, s77, -v50
	v_add_f32_e32 v55, v52, v55
	v_exp_f32_e32 v57, v57
	v_fma_f32 v58, v188, s77, -v50
	v_add_f32_e32 v55, v53, v55
	v_exp_f32_e32 v58, v58
	v_fma_f32 v59, v186, s77, -v50
	v_add_f32_e32 v55, v54, v55
	v_exp_f32_e32 v59, v59
	v_fma_f32 v60, v185, s77, -v50
	v_add_f32_e32 v55, v56, v55
	v_exp_f32_e32 v60, v60
	v_fma_f32 v61, v183, s77, -v50
	v_add_f32_e32 v55, v57, v55
	v_exp_f32_e32 v61, v61
	v_fma_f32 v62, v184, s77, -v50
	v_add_f32_e32 v55, v58, v55
	v_exp_f32_e32 v62, v62
	v_fma_f32 v63, v182, s77, -v50
	v_add_f32_e32 v55, v59, v55
	v_exp_f32_e32 v63, v63
	v_fma_f32 v176, v181, s77, -v50
	v_add_f32_e32 v55, v60, v55
	v_exp_f32_e32 v193, v176
	v_fma_f32 v176, v179, s77, -v50
	v_add_f32_e32 v55, v61, v55
	v_exp_f32_e32 v195, v176
	v_fma_f32 v176, v180, s77, -v50
	v_add_f32_e32 v55, v62, v55
	v_exp_f32_e32 v196, v176
	v_fma_f32 v176, v178, s77, -v50
	v_add_f32_e32 v55, v63, v55
	v_exp_f32_e32 v197, v176
	v_fma_f32 v0, v0, s77, -v50
	v_add_f32_e32 v55, v193, v55
	v_exp_f32_e32 v198, v0
	v_fma_f32 v0, v1, s77, -v50
	v_add_f32_e32 v55, v195, v55
	v_exp_f32_e32 v199, v0
	v_fma_f32 v0, v2, s77, -v50
	v_add_f32_e32 v55, v196, v55
	v_exp_f32_e32 v200, v0
	v_fma_f32 v0, v3, s77, -v50
	v_add_f32_e32 v55, v197, v55
	v_exp_f32_e32 v201, v0
	v_fma_f32 v1, v4, s77, -v50
	v_add_f32_e32 v0, v198, v55
	v_exp_f32_e32 v202, v1
	v_fma_f32 v1, v5, s77, -v50
	v_add_f32_e32 v0, v199, v0
	v_exp_f32_e32 v203, v1
	v_fma_f32 v1, v6, s77, -v50
	v_add_f32_e32 v0, v200, v0
	v_exp_f32_e32 v204, v1
	v_fma_f32 v1, v7, s77, -v50
	v_add_f32_e32 v0, v201, v0
	v_exp_f32_e32 v205, v1
	v_fma_f32 v1, v8, s77, -v50
	v_add_f32_e32 v0, v202, v0
	v_exp_f32_e32 v206, v1
	v_fma_f32 v1, v9, s77, -v50
	v_add_f32_e32 v0, v203, v0
	v_exp_f32_e32 v207, v1
	v_fma_f32 v1, v10, s77, -v50
	v_add_f32_e32 v0, v204, v0
	v_exp_f32_e32 v208, v1
	v_fma_f32 v1, v11, s77, -v50
	v_add_f32_e32 v0, v205, v0
	v_exp_f32_e32 v209, v1
	v_fma_f32 v1, v12, s77, -v50
	v_add_f32_e32 v0, v206, v0
	v_exp_f32_e32 v210, v1
	v_fma_f32 v1, v13, s77, -v50
	v_add_f32_e32 v0, v207, v0
	v_exp_f32_e32 v211, v1
	v_fma_f32 v1, v14, s77, -v50
	v_add_f32_e32 v0, v208, v0
	v_exp_f32_e32 v212, v1
	v_fma_f32 v1, v15, s77, -v50
	v_add_f32_e32 v0, v209, v0
	v_exp_f32_e32 v213, v1
	v_fma_f32 v1, v32, s77, -v50
	v_add_f32_e32 v0, v210, v0
	v_exp_f32_e32 v214, v1
	v_fma_f32 v1, v33, s77, -v50
	v_add_f32_e32 v0, v211, v0
	v_exp_f32_e32 v215, v1
	v_fma_f32 v1, v34, s77, -v50
	v_add_f32_e32 v0, v212, v0
	v_exp_f32_e32 v216, v1
	v_fma_f32 v1, v35, s77, -v50
	v_add_f32_e32 v0, v213, v0
	v_exp_f32_e32 v217, v1
	v_fma_f32 v1, v36, s77, -v50
	v_add_f32_e32 v0, v214, v0
	v_exp_f32_e32 v218, v1
	v_fma_f32 v1, v37, s77, -v50
	v_add_f32_e32 v0, v215, v0
	v_exp_f32_e32 v219, v1
	v_fma_f32 v1, v38, s77, -v50
	v_add_f32_e32 v0, v216, v0
	v_exp_f32_e32 v220, v1
	v_fma_f32 v1, v39, s77, -v50
	v_add_f32_e32 v0, v217, v0
	v_exp_f32_e32 v221, v1
	v_fma_f32 v1, v40, s77, -v50
	v_add_f32_e32 v0, v218, v0
	v_exp_f32_e32 v222, v1
	v_fma_f32 v1, v41, s77, -v50
	v_add_f32_e32 v0, v219, v0
	v_exp_f32_e32 v223, v1
	v_fma_f32 v1, v42, s77, -v50
	v_add_f32_e32 v0, v220, v0
	v_exp_f32_e32 v224, v1
	v_fma_f32 v1, v43, s77, -v50
	v_add_f32_e32 v0, v221, v0
	v_exp_f32_e32 v225, v1
	v_fma_f32 v1, v44, s77, -v50
	v_add_f32_e32 v0, v222, v0
	v_exp_f32_e32 v226, v1
	v_fma_f32 v1, v45, s77, -v50
	v_add_f32_e32 v0, v223, v0
	v_exp_f32_e32 v227, v1
	v_fma_f32 v1, v46, s77, -v50
	v_add_f32_e32 v0, v224, v0
	v_exp_f32_e32 v228, v1
	v_fma_f32 v1, v47, s77, -v50
	v_add_f32_e32 v0, v225, v0
	v_exp_f32_e32 v229, v1
	v_fma_f32 v1, v64, s77, -v50
	v_add_f32_e32 v0, v226, v0
	v_exp_f32_e32 v230, v1
	v_fma_f32 v1, v65, s77, -v50
	v_add_f32_e32 v0, v227, v0
	v_exp_f32_e32 v231, v1
	v_fma_f32 v1, v66, s77, -v50
	v_add_f32_e32 v0, v228, v0
	v_exp_f32_e32 v232, v1
	v_fma_f32 v1, v68, s77, -v50
	v_add_f32_e32 v0, v229, v0
	v_exp_f32_e32 v233, v1
	v_fma_f32 v1, v67, s77, -v50
	v_add_f32_e32 v0, v230, v0
	v_exp_f32_e32 v234, v1
	v_fma_f32 v1, v69, s77, -v50
	v_add_f32_e32 v0, v231, v0
	v_exp_f32_e32 v235, v1
	v_fma_f32 v1, v71, s77, -v50
	v_add_f32_e32 v0, v232, v0
	v_exp_f32_e32 v236, v1
	v_fma_f32 v1, v73, s77, -v50
	v_add_f32_e32 v0, v233, v0
	v_exp_f32_e32 v237, v1
	v_fma_f32 v1, v72, s77, -v50
	v_add_f32_e32 v0, v234, v0
	v_exp_f32_e32 v186, v1
	v_fma_f32 v1, v74, s77, -v50
	v_add_f32_e32 v0, v235, v0
	v_exp_f32_e32 v187, v1
	v_fma_f32 v1, v75, s77, -v50
	v_add_f32_e32 v0, v236, v0
	v_exp_f32_e32 v188, v1
	v_fma_f32 v1, v77, s77, -v50
	v_add_f32_e32 v0, v237, v0
	v_exp_f32_e32 v189, v1
	v_fma_f32 v1, v76, s77, -v50
	v_add_f32_e32 v0, v186, v0
	v_exp_f32_e32 v190, v1
	v_fma_f32 v1, v78, s77, -v50
	v_add_f32_e32 v0, v187, v0
	v_exp_f32_e32 v191, v1
	v_fma_f32 v1, v79, s77, -v50
	v_add_f32_e32 v0, v188, v0
	v_exp_f32_e32 v192, v1
	v_fma_f32 v1, v194, s77, -v50
	v_add_f32_e32 v0, v189, v0
	v_exp_f32_e32 v194, v1
	v_fma_f32 v1, v16, s77, -v50
	v_add_f32_e32 v0, v190, v0
	v_exp_f32_e32 v178, v1
	v_fma_f32 v1, v17, s77, -v50
	v_add_f32_e32 v0, v191, v0
	v_exp_f32_e32 v179, v1
	v_fma_f32 v1, v18, s77, -v50
	v_add_f32_e32 v0, v192, v0
	v_exp_f32_e32 v180, v1
	v_fma_f32 v1, v19, s77, -v50
	v_add_f32_e32 v0, v194, v0
	v_exp_f32_e32 v181, v1
	v_fma_f32 v1, v20, s77, -v50
	v_add_f32_e32 v0, v178, v0
	v_exp_f32_e32 v182, v1
	v_fma_f32 v1, v21, s77, -v50
	v_add_f32_e32 v0, v179, v0
	v_exp_f32_e32 v183, v1
	v_fma_f32 v1, v22, s77, -v50
	v_add_f32_e32 v0, v180, v0
	v_exp_f32_e32 v184, v1
	v_fma_f32 v1, v23, s77, -v50
	v_add_f32_e32 v0, v181, v0
	v_exp_f32_e32 v185, v1
	v_fma_f32 v1, v24, s77, -v50
	v_add_f32_e32 v0, v182, v0
	v_exp_f32_e32 v73, v1
	v_fma_f32 v1, v25, s77, -v50
	v_add_f32_e32 v0, v183, v0
	v_exp_f32_e32 v74, v1
	v_fma_f32 v1, v26, s77, -v50
	v_add_f32_e32 v0, v184, v0
	v_exp_f32_e32 v75, v1
	v_fma_f32 v1, v27, s77, -v50
	v_add_f32_e32 v0, v185, v0
	v_exp_f32_e32 v77, v1
	v_fma_f32 v1, v28, s77, -v50
	v_add_f32_e32 v0, v73, v0
	v_exp_f32_e32 v78, v1
	v_fma_f32 v1, v29, s77, -v50
	v_add_f32_e32 v0, v74, v0
	v_exp_f32_e32 v79, v1
	v_fma_f32 v1, v30, s77, -v50
	v_add_f32_e32 v0, v75, v0
	v_exp_f32_e32 v176, v1
	v_fma_f32 v1, v31, s77, -v50
	v_add_f32_e32 v0, v77, v0
	v_exp_f32_e32 v177, v1
	v_add_f32_e32 v0, v78, v0
	v_add_f32_e32 v0, v79, v0
	v_add_f32_e32 v0, v176, v0
	v_add_f32_e32 v71, v177, v0
	v_mov_b32_e32 v72, v71
	s_nop 1
	v_permlane32_swap_b32_e32 v71, v72
	v_add_u32_e32 v0, 64, v172
	v_lshrrev_b32_e32 v0, 3, v0
	v_mad_u64_u32 v[64:65], s[0:1], v0, s76, v[168:169]
	v_add_u32_e32 v0, 0x80, v172
	v_lshrrev_b32_e32 v0, 3, v0
	v_mad_u64_u32 v[66:67], s[0:1], v0, s76, v[168:169]
	v_add_u32_e32 v0, 0xc0, v172
	v_lshrrev_b32_e32 v0, 3, v0
	v_mad_u64_u32 v[68:69], s[0:1], v0, s76, v[168:169]
	v_add3_u32 v76, s72, v48, v49
	s_waitcnt vmcnt(23)
	ds_write_b128 v175, v[140:143]
	s_waitcnt vmcnt(22)
	ds_write_b128 v64, v[136:139]
	s_waitcnt vmcnt(21)
	ds_write_b128 v66, v[132:135]
	s_waitcnt vmcnt(20)
	ds_write_b128 v68, v[128:131]
	ds_read_b64_tr_b16 v[0:1], v76
	ds_read_b64_tr_b16 v[2:3], v76 offset:1152
	ds_read_b64_tr_b16 v[10:11], v76 offset:1216
	ds_read_b64_tr_b16 v[8:9], v76 offset:64
	v_cvt_pk_bf16_f32 v4, v51, v52
	v_cvt_pk_bf16_f32 v5, v53, v54
	v_cvt_pk_bf16_f32 v6, v56, v57
	v_cvt_pk_bf16_f32 v7, v58, v59
	ds_read_b64_tr_b16 v[32:33], v76 offset:2304
	ds_read_b64_tr_b16 v[34:35], v76 offset:3456
	s_waitcnt lgkmcnt(4)
	v_mfma_f32_32x32x16_bf16 v[16:31], v[0:3], v[4:7], 0
	ds_read_b64_tr_b16 v[42:43], v76 offset:3520
	ds_read_b64_tr_b16 v[40:41], v76 offset:2368
	v_cvt_pk_bf16_f32 v36, v60, v61
	v_cvt_pk_bf16_f32 v37, v62, v63
	v_cvt_pk_bf16_f32 v38, v193, v195
	v_cvt_pk_bf16_f32 v39, v196, v197
	s_waitcnt lgkmcnt(4)
	v_mfma_f32_32x32x16_bf16 v[0:15], v[8:11], v[4:7], 0
	s_waitcnt lgkmcnt(2)
	v_mfma_f32_32x32x16_bf16 v[16:31], v[32:35], v[36:39], v[16:31]
	s_waitcnt lgkmcnt(0)
	v_mfma_f32_32x32x16_bf16 v[0:15], v[40:43], v[36:39], v[0:15]
	v_lshl_add_u64 v[32:33], s[42:43], 0, v[144:145]
	v_lshl_add_u64 v[34:35], s[42:43], 0, v[154:155]
	global_load_dwordx4 v[48:51], v[32:33], off
	global_load_dwordx4 v[52:55], v[34:35], off
	v_lshl_add_u64 v[32:33], s[42:43], 0, v[156:157]
	v_lshl_add_u64 v[34:35], s[42:43], 0, v[158:159]
	global_load_dwordx4 v[56:59], v[32:33], off
	global_load_dwordx4 v[60:63], v[34:35], off
	v_lshl_add_u64 v[32:33], s[42:43], 0, v[160:161]
	v_lshl_add_u64 v[36:37], s[42:43], 0, v[162:163]
	v_lshl_add_u64 v[40:41], s[42:43], 0, v[164:165]
	v_lshl_add_u64 v[44:45], s[42:43], 0, v[166:167]
	global_load_dwordx4 v[32:35], v[32:33], off
	s_nop 0
	global_load_dwordx4 v[36:39], v[36:37], off
	s_nop 0
	global_load_dwordx4 v[40:43], v[40:41], off
	s_nop 0
	global_load_dwordx4 v[44:47], v[44:45], off
	s_waitcnt vmcnt(27)
	ds_write_b128 v175, v[112:115]
	s_waitcnt vmcnt(26)
	ds_write_b128 v64, v[116:119]
	s_waitcnt vmcnt(25)
	ds_write_b128 v66, v[120:123]
	s_waitcnt vmcnt(24)
	ds_write_b128 v68, v[124:127]
	ds_read_b64_tr_b16 v[116:117], v76
	ds_read_b64_tr_b16 v[118:119], v76 offset:1152
	ds_read_b64_tr_b16 v[120:121], v76 offset:64
	ds_read_b64_tr_b16 v[122:123], v76 offset:1216
	v_cvt_pk_bf16_f32 v112, v198, v199
	v_cvt_pk_bf16_f32 v113, v200, v201
	v_cvt_pk_bf16_f32 v114, v202, v203
	v_cvt_pk_bf16_f32 v115, v204, v205
	s_waitcnt lgkmcnt(2)
	s_nop 0
	v_mfma_f32_32x32x16_bf16 v[16:31], v[116:119], v[112:115], v[16:31]
	s_waitcnt lgkmcnt(0)
	v_mfma_f32_32x32x16_bf16 v[0:15], v[120:123], v[112:115], v[0:15]
	ds_read_b64_tr_b16 v[116:117], v76 offset:2304
	ds_read_b64_tr_b16 v[118:119], v76 offset:3456
	ds_read_b64_tr_b16 v[120:121], v76 offset:2368
	ds_read_b64_tr_b16 v[122:123], v76 offset:3520
	v_cvt_pk_bf16_f32 v112, v206, v207
	v_cvt_pk_bf16_f32 v113, v208, v209
	v_cvt_pk_bf16_f32 v114, v210, v211
	v_cvt_pk_bf16_f32 v115, v212, v213
	s_waitcnt lgkmcnt(2)
	s_nop 0
	v_mfma_f32_32x32x16_bf16 v[16:31], v[116:119], v[112:115], v[16:31]
	s_waitcnt lgkmcnt(0)
	v_mfma_f32_32x32x16_bf16 v[0:15], v[120:123], v[112:115], v[0:15]
	s_waitcnt vmcnt(23)
	ds_write_b128 v175, v[96:99]
	s_waitcnt vmcnt(22)
	ds_write_b128 v64, v[100:103]
	s_waitcnt vmcnt(21)
	ds_write_b128 v66, v[104:107]
	s_waitcnt vmcnt(20)
	ds_write_b128 v68, v[108:111]
	ds_read_b64_tr_b16 v[100:101], v76
	ds_read_b64_tr_b16 v[102:103], v76 offset:1152
	ds_read_b64_tr_b16 v[104:105], v76 offset:64
	ds_read_b64_tr_b16 v[106:107], v76 offset:1216
	v_cvt_pk_bf16_f32 v96, v214, v215
	v_cvt_pk_bf16_f32 v97, v216, v217
	v_cvt_pk_bf16_f32 v98, v218, v219
	v_cvt_pk_bf16_f32 v99, v220, v221
	s_waitcnt lgkmcnt(2)
	s_nop 0
	v_mfma_f32_32x32x16_bf16 v[16:31], v[100:103], v[96:99], v[16:31]
	s_waitcnt lgkmcnt(0)
	v_mfma_f32_32x32x16_bf16 v[0:15], v[104:107], v[96:99], v[0:15]
	ds_read_b64_tr_b16 v[100:101], v76 offset:2304
	ds_read_b64_tr_b16 v[102:103], v76 offset:3456
	ds_read_b64_tr_b16 v[104:105], v76 offset:2368
	ds_read_b64_tr_b16 v[106:107], v76 offset:3520
	v_cvt_pk_bf16_f32 v96, v222, v223
	v_cvt_pk_bf16_f32 v97, v224, v225
	v_cvt_pk_bf16_f32 v98, v226, v227
	v_cvt_pk_bf16_f32 v99, v228, v229
	s_waitcnt lgkmcnt(2)
	s_nop 0
	v_mfma_f32_32x32x16_bf16 v[16:31], v[100:103], v[96:99], v[16:31]
	s_waitcnt lgkmcnt(0)
	v_mfma_f32_32x32x16_bf16 v[0:15], v[104:107], v[96:99], v[0:15]
	s_waitcnt vmcnt(7)
	ds_write_b128 v175, v[48:51]
	s_waitcnt vmcnt(6)
	ds_write_b128 v64, v[52:55]
	s_waitcnt vmcnt(5)
	ds_write_b128 v66, v[56:59]
	s_waitcnt vmcnt(4)
	ds_write_b128 v68, v[60:63]
	ds_read_b64_tr_b16 v[52:53], v76
	ds_read_b64_tr_b16 v[54:55], v76 offset:1152
	ds_read_b64_tr_b16 v[56:57], v76 offset:64
	ds_read_b64_tr_b16 v[58:59], v76 offset:1216
	v_cvt_pk_bf16_f32 v48, v230, v231
	v_cvt_pk_bf16_f32 v49, v232, v233
	v_cvt_pk_bf16_f32 v50, v234, v235
	v_cvt_pk_bf16_f32 v51, v236, v237
	s_waitcnt lgkmcnt(2)
	s_nop 0
	v_mfma_f32_32x32x16_bf16 v[16:31], v[52:55], v[48:51], v[16:31]
	s_waitcnt lgkmcnt(0)
	v_mfma_f32_32x32x16_bf16 v[0:15], v[56:59], v[48:51], v[0:15]
	ds_read_b64_tr_b16 v[52:53], v76 offset:2304
	ds_read_b64_tr_b16 v[54:55], v76 offset:3456
	ds_read_b64_tr_b16 v[56:57], v76 offset:2368
	ds_read_b64_tr_b16 v[58:59], v76 offset:3520
	v_cvt_pk_bf16_f32 v48, v186, v187
	v_cvt_pk_bf16_f32 v49, v188, v189
	v_cvt_pk_bf16_f32 v50, v190, v191
	v_cvt_pk_bf16_f32 v51, v192, v194
	s_waitcnt lgkmcnt(2)
	s_nop 0
	v_mfma_f32_32x32x16_bf16 v[16:31], v[52:55], v[48:51], v[16:31]
	s_waitcnt lgkmcnt(0)
	v_mfma_f32_32x32x16_bf16 v[0:15], v[56:59], v[48:51], v[0:15]
	s_waitcnt vmcnt(3)
	ds_write_b128 v175, v[32:35]
	s_waitcnt vmcnt(2)
	ds_write_b128 v64, v[36:39]
	s_waitcnt vmcnt(1)
	ds_write_b128 v66, v[40:43]
	s_waitcnt vmcnt(0)
	ds_write_b128 v68, v[44:47]
	ds_read_b64_tr_b16 v[36:37], v76
	ds_read_b64_tr_b16 v[38:39], v76 offset:1152
	ds_read_b64_tr_b16 v[40:41], v76 offset:64
	ds_read_b64_tr_b16 v[42:43], v76 offset:1216
	v_cvt_pk_bf16_f32 v32, v178, v179
	v_cvt_pk_bf16_f32 v33, v180, v181
	v_cvt_pk_bf16_f32 v34, v182, v183
	v_cvt_pk_bf16_f32 v35, v184, v185
	s_waitcnt lgkmcnt(2)
	s_nop 0
	v_mfma_f32_32x32x16_bf16 v[16:31], v[36:39], v[32:35], v[16:31]
	s_waitcnt lgkmcnt(0)
	v_mfma_f32_32x32x16_bf16 v[0:15], v[40:43], v[32:35], v[0:15]
	ds_read_b64_tr_b16 v[36:37], v76 offset:2304
	ds_read_b64_tr_b16 v[38:39], v76 offset:3456
	ds_read_b64_tr_b16 v[40:41], v76 offset:2368
	ds_read_b64_tr_b16 v[42:43], v76 offset:3520
	v_cvt_pk_bf16_f32 v32, v73, v74
	v_cvt_pk_bf16_f32 v33, v75, v77
	v_cvt_pk_bf16_f32 v35, v176, v177
	v_cvt_pk_bf16_f32 v34, v78, v79
	s_waitcnt lgkmcnt(2)
	s_nop 0
	v_mfma_f32_32x32x16_bf16 v[16:31], v[36:39], v[32:35], v[16:31]
	v_lshl_add_u64 v[44:45], s[18:19], 0, v[146:147]
	global_store_dwordx4 v[44:45], v[84:87], off
	v_lshl_add_u64 v[44:45], s[18:19], 0, v[148:149]
	global_store_dwordx4 v[44:45], v[80:83], off
	v_lshl_add_u64 v[44:45], s[18:19], 0, v[150:151]
	global_store_dwordx4 v[44:45], v[92:95], off
	v_lshl_add_u64 v[44:45], s[18:19], 0, v[152:153]
	s_waitcnt lgkmcnt(0)
	v_mfma_f32_32x32x16_bf16 v[0:15], v[40:43], v[32:35], v[0:15]
	v_add_f32_e32 v33, v71, v72
	v_div_scale_f32 v32, s[0:1], v33, v33, 1.0
	v_rcp_f32_e32 v34, v32
	global_store_dwordx4 v[44:45], v[88:91], off
	v_fma_f32 v35, -v32, v34, 1.0
	v_fmac_f32_e32 v34, v35, v34
	v_div_scale_f32 v35, vcc, 1.0, v33, 1.0
	v_mul_f32_e32 v36, v35, v34
	v_fma_f32 v37, -v32, v36, v35
	v_fmac_f32_e32 v36, v37, v34
	v_fma_f32 v32, -v32, v36, v35
	v_log_f32_e32 v35, v33
	v_div_fmas_f32 v32, v32, v34, v36
	v_div_fixup_f32 v32, v32, v33, 1.0
	v_subrev_u32_e32 v33, s84, v174
	v_cndmask_b32_e64 v34, 0, 1, s[54:55]
	v_fmac_f32_e32 v35, 0x3e38aa3b, v70
	v_cmp_ne_u32_e64 s[38:39], 1, v34
	s_andn2_b64 vcc, exec, s[54:55]
	v_lshl_add_u32 v36, v33, 2, 0
	s_cbranch_vccnz .LBB0_358
	v_add_u32_e32 v34, 0x12000, v36
	ds_read_b32 v34, v34
	v_max_f32_e32 v37, v35, v35
	s_waitcnt lgkmcnt(0)
	v_max_f32_e32 v38, v34, v34
	v_max_f32_e32 v37, v38, v37
	v_sub_f32_e32 v38, v34, v37
	v_sub_f32_e32 v39, v35, v37
	v_exp_f32_e32 v38, v38
	v_exp_f32_e32 v39, v39
	s_nop 0
	v_add_f32_e32 v38, v38, v39
	v_log_f32_e32 v38, v38
	s_nop 0
	v_add_f32_e32 v37, v37, v38
	v_sub_f32_e32 v35, v35, v37
	v_exp_f32_e32 v35, v35
	v_sub_f32_e32 v34, v34, v37
	v_exp_f32_e32 v34, v34
	v_mul_f32_e32 v32, v32, v35
	v_mov_b32_e32 v35, v37
	s_branch .LBB0_359
